# v166 + P1: leading half's ALIGN drain barrier moved after its first two output stores (same as done for P9)
# speedup vs baseline: 1.0063x; 1.0004x over previous
.LBB0_118:
	v_lshl_add_u32 v146, s40, 8, v148
	v_or_b32_e32 v158, 16, v146
	v_ashrrev_i32_e32 v147, 31, v146
	v_ashrrev_i32_e32 v159, 31, v158
	v_or_b32_e32 v162, 32, v146
	v_lshl_add_u64 v[154:155], v[146:147], 2, s[12:13]
	v_lshl_add_u64 v[144:145], v[158:159], 2, s[12:13]
	v_ashrrev_i32_e32 v163, 31, v162
	v_or_b32_e32 v166, 48, v146
	global_load_dword v156, v[154:155], off
	global_load_dword v160, v[144:145], off
	v_lshl_add_u64 v[144:145], v[162:163], 2, s[12:13]
	v_ashrrev_i32_e32 v167, 31, v166
	global_load_dword v164, v[144:145], off
	v_lshl_add_u64 v[144:145], v[166:167], 2, s[12:13]
	global_load_dword v168, v[144:145], off
	v_lshl_or_b32 v170, s81, 8, v150
	v_mov_b64_e32 v[144:145], s[16:17]
	v_ashrrev_i32_e32 v171, 31, v170
	v_add_u32_e32 v161, 0x80, v146
	v_add_u32_e32 v165, 0x90, v146
	v_add_u32_e32 v167, 0xa0, v146
	v_add_u32_e32 v169, 0xb0, v146
	v_mad_i64_i32 v[172:173], s[64:65], v146, s80, v[144:145]
	v_lshlrev_b64 v[146:147], 1, v[170:171]
	v_lshl_add_u64 v[170:171], v[172:173], 0, v[146:147]
	global_load_dword v172, v[154:155], off offset:512
	global_load_dword v174, v[154:155], off offset:576
	global_load_dword v176, v[154:155], off offset:640
	s_nop 0
	global_load_dword v154, v[154:155], off offset:704
	v_mad_i64_i32 v[158:159], s[64:65], v158, s80, v[144:145]
	v_mad_i64_i32 v[162:163], s[64:65], v162, s80, v[144:145]
	v_lshl_add_u64 v[158:159], v[158:159], 0, v[146:147]
	v_lshl_add_u64 v[162:163], v[162:163], 0, v[146:147]
	s_andn2_b64 vcc, exec, s[4:5]
	s_mov_b64 s[4:5], -1
	s_waitcnt vmcnt(0)
	v_pk_mul_f32 v[126:127], v[126:127], v[156:157] op_sel_hi:[1,0]
	v_pk_mul_f32 v[124:125], v[124:125], v[156:157] op_sel_hi:[1,0]
	v_pk_mul_f32 v[122:123], v[122:123], v[156:157] op_sel_hi:[1,0]
	v_pk_mul_f32 v[120:121], v[120:121], v[156:157] op_sel_hi:[1,0]
	v_pk_mul_f32 v[118:119], v[118:119], v[160:161] op_sel_hi:[1,0]
	v_pk_mul_f32 v[116:117], v[116:117], v[160:161] op_sel_hi:[1,0]
	v_pk_mul_f32 v[114:115], v[114:115], v[160:161] op_sel_hi:[1,0]
	v_pk_mul_f32 v[112:113], v[112:113], v[160:161] op_sel_hi:[1,0]
	v_pk_mul_f32 v[110:111], v[110:111], v[156:157] op_sel_hi:[1,0]
	v_pk_mul_f32 v[108:109], v[108:109], v[156:157] op_sel_hi:[1,0]
	v_pk_mul_f32 v[178:179], v[106:107], v[156:157] op_sel_hi:[1,0]
	v_pk_mul_f32 v[156:157], v[104:105], v[156:157] op_sel_hi:[1,0]
	v_cvt_pk_bf16_f32 v104, v124, v125
	v_cvt_pk_bf16_f32 v105, v126, v127
	v_cvt_pk_bf16_f32 v106, v120, v121
	v_cvt_pk_bf16_f32 v107, v122, v123
	v_pk_mul_f32 v[94:95], v[94:95], v[160:161] op_sel_hi:[1,0]
	v_pk_mul_f32 v[92:93], v[92:93], v[160:161] op_sel_hi:[1,0]
	v_pk_mul_f32 v[90:91], v[90:91], v[160:161] op_sel_hi:[1,0]
	v_pk_mul_f32 v[88:89], v[88:89], v[160:161] op_sel_hi:[1,0]
	v_pk_mul_f32 v[102:103], v[102:103], v[164:165] op_sel_hi:[1,0]
	v_pk_mul_f32 v[100:101], v[100:101], v[164:165] op_sel_hi:[1,0]
	v_pk_mul_f32 v[98:99], v[98:99], v[164:165] op_sel_hi:[1,0]
	v_pk_mul_f32 v[96:97], v[96:97], v[164:165] op_sel_hi:[1,0]
	v_pk_mul_f32 v[124:125], v[82:83], v[164:165] op_sel_hi:[1,0]
	v_pk_mul_f32 v[126:127], v[80:81], v[164:165] op_sel_hi:[1,0]
	v_cvt_pk_bf16_f32 v80, v116, v117
	v_cvt_pk_bf16_f32 v81, v118, v119
	v_cvt_pk_bf16_f32 v82, v112, v113
	v_cvt_pk_bf16_f32 v83, v114, v115
	v_cvt_pk_bf16_f32 v108, v108, v109
	v_cvt_pk_bf16_f32 v109, v110, v111
	v_cvt_pk_bf16_f32 v110, v156, v157
	v_cvt_pk_bf16_f32 v111, v178, v179
	v_pk_mul_f32 v[120:121], v[86:87], v[164:165] op_sel_hi:[1,0]
	v_pk_mul_f32 v[122:123], v[84:85], v[164:165] op_sel_hi:[1,0]
	global_store_dwordx4 v[170:171], v[104:107], off
	global_store_dwordx4 v[170:171], v[108:111], off offset:256
	s_cmp_lg_u64 s[22:23], 0
	s_cbranch_scc0 .Lp1_latebar
	s_barrier
.Lp1_latebar:
	v_cvt_pk_bf16_f32 v84, v92, v93
	v_cvt_pk_bf16_f32 v85, v94, v95
	v_cvt_pk_bf16_f32 v86, v88, v89
	v_cvt_pk_bf16_f32 v87, v90, v91
	v_cvt_pk_bf16_f32 v88, v100, v101
	v_cvt_pk_bf16_f32 v89, v102, v103
	v_cvt_pk_bf16_f32 v90, v96, v97
	v_cvt_pk_bf16_f32 v91, v98, v99
	global_store_dwordx4 v[158:159], v[80:83], off
	global_store_dwordx4 v[158:159], v[84:87], off offset:256
	global_store_dwordx4 v[162:163], v[88:91], off
	v_mad_i64_i32 v[80:81], s[64:65], v166, s80, v[144:145]
	v_pk_mul_f32 v[78:79], v[78:79], v[168:169] op_sel_hi:[1,0]
	v_pk_mul_f32 v[76:77], v[76:77], v[168:169] op_sel_hi:[1,0]
	v_pk_mul_f32 v[82:83], v[74:75], v[168:169] op_sel_hi:[1,0]
	v_pk_mul_f32 v[74:75], v[72:73], v[168:169] op_sel_hi:[1,0]
	v_lshl_add_u64 v[80:81], v[80:81], 0, v[146:147]
	v_cvt_pk_bf16_f32 v72, v76, v77
	v_cvt_pk_bf16_f32 v73, v78, v79
	v_cvt_pk_bf16_f32 v74, v74, v75
	v_cvt_pk_bf16_f32 v75, v82, v83
	global_store_dwordx4 v[80:81], v[72:75], off
	v_pk_mul_f32 v[70:71], v[70:71], v[168:169] op_sel_hi:[1,0]
	v_pk_mul_f32 v[68:69], v[68:69], v[168:169] op_sel_hi:[1,0]
	v_pk_mul_f32 v[72:73], v[66:67], v[168:169] op_sel_hi:[1,0]
	v_pk_mul_f32 v[66:67], v[64:65], v[168:169] op_sel_hi:[1,0]
	v_cvt_pk_bf16_f32 v64, v68, v69
	v_cvt_pk_bf16_f32 v65, v70, v71
	v_cvt_pk_bf16_f32 v66, v66, v67
	v_cvt_pk_bf16_f32 v67, v72, v73
	global_store_dwordx4 v[80:81], v[64:67], off offset:256
	v_pk_mul_f32 v[62:63], v[62:63], v[172:173] op_sel_hi:[1,0]
	v_pk_mul_f32 v[60:61], v[60:61], v[172:173] op_sel_hi:[1,0]
	v_mad_i64_i32 v[64:65], s[64:65], v161, s80, v[144:145]
	v_pk_mul_f32 v[66:67], v[58:59], v[172:173] op_sel_hi:[1,0]
	v_pk_mul_f32 v[58:59], v[56:57], v[172:173] op_sel_hi:[1,0]
	v_lshl_add_u64 v[64:65], v[64:65], 0, v[146:147]
	v_cvt_pk_bf16_f32 v56, v60, v61
	v_cvt_pk_bf16_f32 v57, v62, v63
	v_cvt_pk_bf16_f32 v58, v58, v59
	v_cvt_pk_bf16_f32 v59, v66, v67
	global_store_dwordx4 v[64:65], v[56:59], off
	v_pk_mul_f32 v[50:51], v[50:51], v[172:173] op_sel_hi:[1,0]
	v_pk_mul_f32 v[48:49], v[48:49], v[172:173] op_sel_hi:[1,0]
	v_pk_mul_f32 v[56:57], v[42:43], v[172:173] op_sel_hi:[1,0]
	v_pk_mul_f32 v[42:43], v[40:41], v[172:173] op_sel_hi:[1,0]
	v_cvt_pk_bf16_f32 v40, v48, v49
	v_cvt_pk_bf16_f32 v41, v50, v51
	v_cvt_pk_bf16_f32 v42, v42, v43
	v_cvt_pk_bf16_f32 v43, v56, v57
	global_store_dwordx4 v[64:65], v[40:43], off offset:256
	v_pk_mul_f32 v[46:47], v[46:47], v[174:175] op_sel_hi:[1,0]
	v_pk_mul_f32 v[44:45], v[44:45], v[174:175] op_sel_hi:[1,0]
	v_mad_i64_i32 v[40:41], s[64:65], v165, s80, v[144:145]
	v_lshl_add_u64 v[48:49], v[40:41], 0, v[146:147]
	v_pk_mul_f32 v[42:43], v[54:55], v[174:175] op_sel_hi:[1,0]
	v_pk_mul_f32 v[40:41], v[52:53], v[174:175] op_sel_hi:[1,0]
	v_pk_mul_f32 v[34:35], v[34:35], v[174:175] op_sel_hi:[1,0]
	v_cvt_pk_bf16_f32 v40, v40, v41
	v_cvt_pk_bf16_f32 v41, v42, v43
	v_cvt_pk_bf16_f32 v42, v44, v45
	v_cvt_pk_bf16_f32 v43, v46, v47
	global_store_dwordx4 v[48:49], v[40:43], off
	v_pk_mul_f32 v[32:33], v[32:33], v[174:175] op_sel_hi:[1,0]
	v_pk_mul_f32 v[30:31], v[30:31], v[176:177] op_sel_hi:[1,0]
	v_pk_mul_f32 v[40:41], v[26:27], v[174:175] op_sel_hi:[1,0]
	v_pk_mul_f32 v[26:27], v[24:25], v[174:175] op_sel_hi:[1,0]
	v_cvt_pk_bf16_f32 v24, v32, v33
	v_cvt_pk_bf16_f32 v25, v34, v35
	v_cvt_pk_bf16_f32 v26, v26, v27
	v_cvt_pk_bf16_f32 v27, v40, v41
	global_store_dwordx4 v[48:49], v[24:27], off offset:256
	v_pk_mul_f32 v[28:29], v[28:29], v[176:177] op_sel_hi:[1,0]
	v_pk_mul_f32 v[18:19], v[18:19], v[176:177] op_sel_hi:[1,0]
	v_mad_i64_i32 v[24:25], s[64:65], v167, s80, v[144:145]
	v_lshl_add_u64 v[32:33], v[24:25], 0, v[146:147]
	v_pk_mul_f32 v[26:27], v[38:39], v[176:177] op_sel_hi:[1,0]
	v_pk_mul_f32 v[24:25], v[36:37], v[176:177] op_sel_hi:[1,0]
	v_pk_mul_f32 v[16:17], v[16:17], v[176:177] op_sel_hi:[1,0]
	v_cvt_pk_bf16_f32 v24, v24, v25
	v_cvt_pk_bf16_f32 v25, v26, v27
	v_cvt_pk_bf16_f32 v26, v28, v29
	v_cvt_pk_bf16_f32 v27, v30, v31
	global_store_dwordx4 v[32:33], v[24:27], off
	v_pk_mul_f32 v[14:15], v[14:15], v[154:155] op_sel_hi:[1,0]
	v_pk_mul_f32 v[12:13], v[12:13], v[154:155] op_sel_hi:[1,0]
	v_pk_mul_f32 v[24:25], v[10:11], v[176:177] op_sel_hi:[1,0]
	v_pk_mul_f32 v[10:11], v[8:9], v[176:177] op_sel_hi:[1,0]
	v_cvt_pk_bf16_f32 v8, v16, v17
	v_cvt_pk_bf16_f32 v9, v18, v19
	v_cvt_pk_bf16_f32 v10, v10, v11
	v_cvt_pk_bf16_f32 v11, v24, v25
	global_store_dwordx4 v[32:33], v[8:11], off offset:256
	v_pk_mul_f32 v[6:7], v[6:7], v[154:155] op_sel_hi:[1,0]
	v_pk_mul_f32 v[4:5], v[4:5], v[154:155] op_sel_hi:[1,0]
	v_mad_i64_i32 v[8:9], s[64:65], v169, s80, v[144:145]
	v_lshl_add_u64 v[16:17], v[8:9], 0, v[146:147]
	v_pk_mul_f32 v[10:11], v[22:23], v[154:155] op_sel_hi:[1,0]
	v_pk_mul_f32 v[8:9], v[20:21], v[154:155] op_sel_hi:[1,0]
	v_cvt_pk_bf16_f32 v92, v122, v123
	v_cvt_pk_bf16_f32 v8, v8, v9
	v_cvt_pk_bf16_f32 v9, v10, v11
	v_cvt_pk_bf16_f32 v10, v12, v13
	v_cvt_pk_bf16_f32 v11, v14, v15
	global_store_dwordx4 v[16:17], v[8:11], off
	v_cvt_pk_bf16_f32 v93, v120, v121
	v_cvt_pk_bf16_f32 v94, v126, v127
	v_pk_mul_f32 v[8:9], v[2:3], v[154:155] op_sel_hi:[1,0]
	v_pk_mul_f32 v[2:3], v[0:1], v[154:155] op_sel_hi:[1,0]
	v_cvt_pk_bf16_f32 v95, v124, v125
	v_cvt_pk_bf16_f32 v0, v4, v5
	v_cvt_pk_bf16_f32 v1, v6, v7
	v_cvt_pk_bf16_f32 v2, v2, v3
	v_cvt_pk_bf16_f32 v3, v8, v9
	global_store_dwordx4 v[162:163], v[92:95], off offset:256
	global_store_dwordx4 v[16:17], v[0:3], off offset:256
	s_cbranch_vccnz .LBB0_111
	s_andn2_b64 vcc, exec, s[0:1]
	s_cbranch_vccnz .LBB0_110
	s_barrier
	s_branch .LBB0_110
